# 2a: next item's TW/AD tiles computed beside the products stage (waves 0-3 before, 4-7 after), stage-L barrier dropped for non-first items
# speedup vs baseline: 1.0068x; 1.0007x over previous
.LBB0_294:
	v_mov_b32_e32 v137, v29
	s_nop 5
	v_cvt_pk_bf16_f32 v48, v78, v79
	v_cvt_pk_bf16_f32 v49, v80, v81
	v_lshl_add_u64 v[26:27], v[26:27], 0, v[136:137]
	global_store_dwordx2 v[26:27], v[48:49], off nt
	v_add_u32_e32 v26, v194, v200
	ds_read_b128 v[78:81], v26
	s_cmp_lg_u32 s51, s72
	s_waitcnt lgkmcnt(0)
	v_mfma_f32_16x16x32_bf16 v[74:77], v[74:77], v[78:81], 0
	ds_read_b128 v[78:81], v26 offset:64
	ds_read_b32 v26, v201
	s_waitcnt lgkmcnt(1)
	v_mfma_f32_16x16x32_bf16 v[70:73], v[70:73], v[78:81], v[74:77]
	s_nop 7
	v_pk_add_f32 v[48:49], v[126:127], v[70:71]
	v_pk_add_f32 v[70:71], v[130:131], v[72:73]
	s_waitcnt lgkmcnt(0)
	v_pk_mul_f32 v[48:49], v[26:27], v[48:49] op_sel_hi:[0,1]
	v_pk_mul_f32 v[26:27], v[26:27], v[70:71] op_sel_hi:[0,1]
	v_cvt_pk_bf16_f32 v48, v48, v49
	v_cvt_pk_bf16_f32 v49, v26, v27
	v_lshl_add_u64 v[26:27], v[124:125], 1, s[26:27]
	global_store_dwordx2 v[26:27], v[48:49], off nt
	v_add_u32_e32 v26, v190, v200
	ds_read_b128 v[70:73], v26
	v_add_u32_e32 v27, v195, v199
	ds_read_b128 v[74:77], v27 offset:10240
	s_waitcnt lgkmcnt(1)
	v_mfma_f32_16x16x32_bf16 v[70:73], v[94:97], v[70:73], 0
	s_waitcnt lgkmcnt(0)
	v_mfma_f32_16x16x32_bf16 v[70:73], v[98:101], v[74:77], v[70:73]
	ds_read_b128 v[74:77], v26 offset:64
	s_waitcnt lgkmcnt(0)
	v_mfma_f32_16x16x32_bf16 v[70:73], v[90:93], v[74:77], v[70:73]
	ds_read_b128 v[74:77], v27 offset:10304
	s_waitcnt lgkmcnt(0)
	v_mfma_f32_16x16x32_bf16 v[70:73], v[86:89], v[74:77], v[70:73]
	s_nop 7
	v_pk_mul_f32 v[26:27], v[68:69], v[72:73]
	v_pk_mul_f32 v[48:49], v[66:67], v[70:71]
	s_nop 0
	v_cvt_pk_bf16_f32 v48, v48, v49
	v_cvt_pk_bf16_f32 v49, v26, v27
	v_lshl_add_u64 v[26:27], v[116:117], 1, s[24:25]
	global_store_dwordx2 v[26:27], v[48:49], off nt
	v_readfirstlane_b32 s36, v0
	s_cmp_lt_u32 s36, 0x100
	s_cbranch_scc1 .Ltw_end
	s_waitcnt vmcnt(8)
.Ltw_do:
	s_cmp_lg_u32 s51, s72
	s_cbranch_scc0 .Ltw_skip
	s_add_i32 s37, s51, s33
	s_and_b32 s37, s37, 1
	v_lshl_add_u32 v47, s37, 9, v180
	ds_read_b128 v[66:69], v47
	ds_read_b128 v[70:73], v47 offset:16
	ds_read_b128 v[74:77], v47 offset:256
	ds_read_b128 v[78:81], v47 offset:272
	v_lshlrev_b32_e32 v26, 16, v2
	v_lshlrev_b32_e32 v49, 16, v6
	v_lshlrev_b32_e32 v48, 16, v10
	v_pk_add_f32 v[48:49], v[48:49], v[26:27] op_sel_hi:[1,0] neg_lo:[0,1] neg_hi:[0,1]
	s_waitcnt lgkmcnt(3)
	v_mov_b32_e32 v82, v66
	s_waitcnt lgkmcnt(1)
	v_mov_b32_e32 v83, v74
	v_pk_mul_f32 v[48:49], v[48:49], v[82:83]
	v_mov_b32_e32 v74, v67
	v_add_f32_e32 v26, v48, v26
	v_add_f32_e32 v26, v26, v49
	v_add_f32_e32 v26, v26, v26
	v_mul_f32_e32 v26, 0x3fb8aa3b, v26
	v_exp_f32_e32 v27, v26
	v_and_b32_e32 v26, 0xffff0000, v2
	v_and_b32_e32 v49, 0xffff0000, v6
	v_and_b32_e32 v48, 0xffff0000, v10
	v_pk_add_f32 v[48:49], v[48:49], v[26:27] op_sel_hi:[1,0] neg_lo:[0,1] neg_hi:[0,1]
	v_mov_b32_e32 v66, v68
	v_pk_mul_f32 v[48:49], v[48:49], v[74:75]
	v_mov_b32_e32 v67, v76
	v_add_f32_e32 v26, v48, v26
	v_add_f32_e32 v26, v26, v49
	v_add_f32_e32 v26, v26, v26
	v_mul_f32_e32 v26, 0x3fb8aa3b, v26
	v_exp_f32_e32 v28, v26
	v_add_f32_e32 v26, 1.0, v27
	v_lshlrev_b32_e32 v49, 16, v7
	v_lshlrev_b32_e32 v48, 16, v11
	v_add_f32_e32 v27, 1.0, v28
	v_lshlrev_b32_e32 v28, 16, v3
	v_pk_add_f32 v[48:49], v[48:49], v[28:29] op_sel_hi:[1,0] neg_lo:[0,1] neg_hi:[0,1]
	v_mov_b32_e32 v76, v69
	v_pk_mul_f32 v[48:49], v[48:49], v[66:67]
	v_lshlrev_b32_e32 v67, 16, v8
	v_add_f32_e32 v28, v48, v28
	v_add_f32_e32 v28, v28, v49
	v_add_f32_e32 v28, v28, v28
	v_mul_f32_e32 v28, 0x3fb8aa3b, v28
	v_exp_f32_e32 v66, v28
	v_and_b32_e32 v28, 0xffff0000, v3
	v_and_b32_e32 v49, 0xffff0000, v7
	v_and_b32_e32 v48, 0xffff0000, v11
	v_pk_add_f32 v[48:49], v[48:49], v[28:29] op_sel_hi:[1,0] neg_lo:[0,1] neg_hi:[0,1]
	v_mov_b32_e32 v68, v70
	v_pk_mul_f32 v[48:49], v[48:49], v[76:77]
	s_waitcnt lgkmcnt(0)
	v_mov_b32_e32 v69, v78
	v_add_f32_e32 v28, v48, v28
	v_add_f32_e32 v28, v28, v49
	v_add_f32_e32 v28, v28, v28
	v_mul_f32_e32 v28, 0x3fb8aa3b, v28
	v_exp_f32_e32 v28, v28
	v_add_f32_e32 v48, 1.0, v66
	v_lshlrev_b32_e32 v66, 16, v12
	v_mov_b32_e32 v78, v71
	v_add_f32_e32 v49, 1.0, v28
	v_lshlrev_b32_e32 v28, 16, v4
	v_pk_add_f32 v[66:67], v[66:67], v[28:29] op_sel_hi:[1,0] neg_lo:[0,1] neg_hi:[0,1]
	v_mov_b32_e32 v70, v72
	v_pk_mul_f32 v[66:67], v[66:67], v[68:69]
	v_lshlrev_b32_e32 v69, 16, v9
	v_add_f32_e32 v28, v66, v28
	v_add_f32_e32 v28, v28, v67
	v_add_f32_e32 v28, v28, v28
	v_mul_f32_e32 v28, 0x3fb8aa3b, v28
	v_exp_f32_e32 v68, v28
	v_and_b32_e32 v28, 0xffff0000, v4
	v_and_b32_e32 v67, 0xffff0000, v8
	v_and_b32_e32 v66, 0xffff0000, v12
	v_pk_add_f32 v[66:67], v[66:67], v[28:29] op_sel_hi:[1,0] neg_lo:[0,1] neg_hi:[0,1]
	v_mov_b32_e32 v71, v80
	v_pk_mul_f32 v[66:67], v[66:67], v[78:79]
	v_mov_b32_e32 v80, v73
	v_add_f32_e32 v28, v66, v28
	v_add_f32_e32 v28, v28, v67
	v_add_f32_e32 v28, v28, v28
	v_mul_f32_e32 v28, 0x3fb8aa3b, v28
	v_exp_f32_e32 v28, v28
	v_add_f32_e32 v66, 1.0, v68
	v_lshlrev_b32_e32 v68, 16, v13
	v_rcp_f32_e32 v26, v26
	v_add_f32_e32 v67, 1.0, v28
	v_lshlrev_b32_e32 v28, 16, v5
	v_pk_add_f32 v[68:69], v[68:69], v[28:29] op_sel_hi:[1,0] neg_lo:[0,1] neg_hi:[0,1]
	v_rcp_f32_e32 v27, v27
	v_pk_mul_f32 v[68:69], v[68:69], v[70:71]
	v_rcp_f32_e32 v48, v48
	v_add_f32_e32 v28, v68, v28
	v_add_f32_e32 v28, v28, v69
	v_add_f32_e32 v28, v28, v28
	v_mul_f32_e32 v28, 0x3fb8aa3b, v28
	v_exp_f32_e32 v70, v28
	v_and_b32_e32 v28, 0xffff0000, v5
	v_and_b32_e32 v69, 0xffff0000, v9
	v_and_b32_e32 v68, 0xffff0000, v13
	v_pk_add_f32 v[68:69], v[68:69], v[28:29] op_sel_hi:[1,0] neg_lo:[0,1] neg_hi:[0,1]
	v_rcp_f32_e32 v49, v49
	v_pk_mul_f32 v[68:69], v[68:69], v[80:81]
	v_rcp_f32_e32 v66, v66
	v_add_f32_e32 v28, v68, v28
	v_add_f32_e32 v28, v28, v69
	v_add_f32_e32 v28, v28, v28
	v_mul_f32_e32 v28, 0x3fb8aa3b, v28
	v_exp_f32_e32 v28, v28
	v_add_f32_e32 v68, 1.0, v70
	v_rcp_f32_e32 v67, v67
	v_rcp_f32_e32 v68, v68
	v_add_f32_e32 v28, 1.0, v28
	v_rcp_f32_e32 v69, v28
	v_pk_fma_f32 v[26:27], v[26:27], 2.0, 1.0 op_sel_hi:[1,0,0] neg_lo:[1,0,0] neg_hi:[1,0,0]
	v_pk_fma_f32 v[48:49], v[48:49], 2.0, 1.0 op_sel_hi:[1,0,0] neg_lo:[1,0,0] neg_hi:[1,0,0]
	v_pk_fma_f32 v[70:71], v[66:67], 2.0, 1.0 op_sel_hi:[1,0,0] neg_lo:[1,0,0] neg_hi:[1,0,0]
	v_pk_fma_f32 v[72:73], v[68:69], 2.0, 1.0 op_sel_hi:[1,0,0] neg_lo:[1,0,0] neg_hi:[1,0,0]
	v_cvt_pk_bf16_f32 v66, v26, v27
	v_cvt_pk_bf16_f32 v67, v48, v49
	v_cvt_pk_bf16_f32 v68, v70, v71
	v_cvt_pk_bf16_f32 v69, v72, v73
	ds_write_b128 v206, v[66:69] offset:32768
	ds_read_b128 v[66:69], v47 offset:1024
	ds_read_b128 v[70:73], v47 offset:1040
	ds_read_b128 v[74:77], v47 offset:1280
	ds_read_b128 v[78:81], v47 offset:1296
	v_lshlrev_b32_e32 v26, 16, v14
	v_and_b32_e32 v27, 0xffff0000, v14
	v_lshlrev_b32_e32 v48, 16, v22
	v_and_b32_e32 v49, 0xffff0000, v22
	v_lshlrev_b32_e32 v82, 16, v18
	v_and_b32_e32 v83, 0xffff0000, v18
	v_pk_add_f32 v[48:49], v[48:49], v[26:27] neg_lo:[0,1] neg_hi:[0,1]
	s_waitcnt lgkmcnt(3)
	v_pk_fma_f32 v[48:49], v[48:49], v[66:67], v[26:27]
	v_pk_add_f32 v[26:27], v[82:83], v[26:27] neg_lo:[0,1] neg_hi:[0,1]
	v_lshlrev_b32_e32 v66, 16, v23
	s_waitcnt lgkmcnt(1)
	v_pk_fma_f32 v[26:27], v[26:27], v[74:75], v[48:49]
	v_lshlrev_b32_e32 v48, 16, v15
	v_and_b32_e32 v49, 0xffff0000, v15
	v_and_b32_e32 v67, 0xffff0000, v23
	v_lshlrev_b32_e32 v74, 16, v19
	v_and_b32_e32 v75, 0xffff0000, v19
	v_pk_add_f32 v[66:67], v[66:67], v[48:49] neg_lo:[0,1] neg_hi:[0,1]
	v_pk_fma_f32 v[66:67], v[66:67], v[68:69], v[48:49]
	v_pk_add_f32 v[48:49], v[74:75], v[48:49] neg_lo:[0,1] neg_hi:[0,1]
	v_lshlrev_b32_e32 v68, 16, v24
	v_pk_fma_f32 v[48:49], v[48:49], v[76:77], v[66:67]
	v_lshlrev_b32_e32 v66, 16, v16
	v_and_b32_e32 v67, 0xffff0000, v16
	v_and_b32_e32 v69, 0xffff0000, v24
	v_lshlrev_b32_e32 v74, 16, v20
	v_and_b32_e32 v75, 0xffff0000, v20
	v_pk_add_f32 v[68:69], v[68:69], v[66:67] neg_lo:[0,1] neg_hi:[0,1]
	v_pk_fma_f32 v[68:69], v[68:69], v[70:71], v[66:67]
	v_pk_add_f32 v[66:67], v[74:75], v[66:67] neg_lo:[0,1] neg_hi:[0,1]
	v_lshlrev_b32_e32 v70, 16, v25
	s_waitcnt lgkmcnt(0)
	v_pk_fma_f32 v[68:69], v[66:67], v[78:79], v[68:69]
	v_lshlrev_b32_e32 v66, 16, v17
	v_and_b32_e32 v67, 0xffff0000, v17
	v_and_b32_e32 v71, 0xffff0000, v25
	v_lshlrev_b32_e32 v74, 16, v21
	v_and_b32_e32 v75, 0xffff0000, v21
	v_pk_add_f32 v[70:71], v[70:71], v[66:67] neg_lo:[0,1] neg_hi:[0,1]
	v_cvt_pk_bf16_f32 v68, v68, v69
	v_pk_fma_f32 v[70:71], v[70:71], v[72:73], v[66:67]
	v_pk_add_f32 v[66:67], v[74:75], v[66:67] neg_lo:[0,1] neg_hi:[0,1]
	v_pk_fma_f32 v[70:71], v[66:67], v[80:81], v[70:71]
	v_cvt_pk_bf16_f32 v66, v26, v27
	v_cvt_pk_bf16_f32 v67, v48, v49
	v_cvt_pk_bf16_f32 v69, v70, v71
	ds_write_b128 v206, v[66:69] offset:43008
.Ltw_skip:
	v_readfirstlane_b32 s36, v0
	s_cmp_lt_u32 s36, 0x100
	s_cbranch_scc1 .Ltw_prod
.Ltw_end:
	s_cmp_lg_u32 s51, s72
	s_waitcnt lgkmcnt(0)
	s_barrier
	s_cbranch_scc0 .LBB0_403

.LBB0_340:
	s_or_b64 exec, exec, s[24:25]
	s_and_b32 s35, s0, 1
	s_cmp_eq_u32 s51, 0
	s_cbranch_scc0 .Ltw_notfirst
	s_waitcnt vmcnt(0)
	v_lshl_add_u32 v47, s35, 9, v180
	ds_read_b128 v[66:69], v47
	ds_read_b128 v[70:73], v47 offset:16
	ds_read_b128 v[74:77], v47 offset:256
	ds_read_b128 v[78:81], v47 offset:272
	v_lshlrev_b32_e32 v26, 16, v2
	v_lshlrev_b32_e32 v49, 16, v6
	v_lshlrev_b32_e32 v48, 16, v10
	v_pk_add_f32 v[48:49], v[48:49], v[26:27] op_sel_hi:[1,0] neg_lo:[0,1] neg_hi:[0,1]
	s_waitcnt lgkmcnt(3)
	v_mov_b32_e32 v82, v66
	s_waitcnt lgkmcnt(1)
	v_mov_b32_e32 v83, v74
	v_pk_mul_f32 v[48:49], v[48:49], v[82:83]
	v_mov_b32_e32 v74, v67
	v_add_f32_e32 v26, v48, v26
	v_add_f32_e32 v26, v26, v49
	v_add_f32_e32 v26, v26, v26
	v_mul_f32_e32 v26, 0x3fb8aa3b, v26
	v_exp_f32_e32 v27, v26
	v_and_b32_e32 v26, 0xffff0000, v2
	v_and_b32_e32 v49, 0xffff0000, v6
	v_and_b32_e32 v48, 0xffff0000, v10
	v_pk_add_f32 v[48:49], v[48:49], v[26:27] op_sel_hi:[1,0] neg_lo:[0,1] neg_hi:[0,1]
	v_mov_b32_e32 v66, v68
	v_pk_mul_f32 v[48:49], v[48:49], v[74:75]
	v_mov_b32_e32 v67, v76
	v_add_f32_e32 v26, v48, v26
	v_add_f32_e32 v26, v26, v49
	v_add_f32_e32 v26, v26, v26
	v_mul_f32_e32 v26, 0x3fb8aa3b, v26
	v_exp_f32_e32 v28, v26
	v_add_f32_e32 v26, 1.0, v27
	v_lshlrev_b32_e32 v49, 16, v7
	v_lshlrev_b32_e32 v48, 16, v11
	v_add_f32_e32 v27, 1.0, v28
	v_lshlrev_b32_e32 v28, 16, v3
	v_pk_add_f32 v[48:49], v[48:49], v[28:29] op_sel_hi:[1,0] neg_lo:[0,1] neg_hi:[0,1]
	v_mov_b32_e32 v76, v69
	v_pk_mul_f32 v[48:49], v[48:49], v[66:67]
	v_lshlrev_b32_e32 v67, 16, v8
	v_add_f32_e32 v28, v48, v28
	v_add_f32_e32 v28, v28, v49
	v_add_f32_e32 v28, v28, v28
	v_mul_f32_e32 v28, 0x3fb8aa3b, v28
	v_exp_f32_e32 v66, v28
	v_and_b32_e32 v28, 0xffff0000, v3
	v_and_b32_e32 v49, 0xffff0000, v7
	v_and_b32_e32 v48, 0xffff0000, v11
	v_pk_add_f32 v[48:49], v[48:49], v[28:29] op_sel_hi:[1,0] neg_lo:[0,1] neg_hi:[0,1]
	v_mov_b32_e32 v68, v70
	v_pk_mul_f32 v[48:49], v[48:49], v[76:77]
	s_waitcnt lgkmcnt(0)
	v_mov_b32_e32 v69, v78
	v_add_f32_e32 v28, v48, v28
	v_add_f32_e32 v28, v28, v49
	v_add_f32_e32 v28, v28, v28
	v_mul_f32_e32 v28, 0x3fb8aa3b, v28
	v_exp_f32_e32 v28, v28
	v_add_f32_e32 v48, 1.0, v66
	v_lshlrev_b32_e32 v66, 16, v12
	v_mov_b32_e32 v78, v71
	v_add_f32_e32 v49, 1.0, v28
	v_lshlrev_b32_e32 v28, 16, v4
	v_pk_add_f32 v[66:67], v[66:67], v[28:29] op_sel_hi:[1,0] neg_lo:[0,1] neg_hi:[0,1]
	v_mov_b32_e32 v70, v72
	v_pk_mul_f32 v[66:67], v[66:67], v[68:69]
	v_lshlrev_b32_e32 v69, 16, v9
	v_add_f32_e32 v28, v66, v28
	v_add_f32_e32 v28, v28, v67
	v_add_f32_e32 v28, v28, v28
	v_mul_f32_e32 v28, 0x3fb8aa3b, v28
	v_exp_f32_e32 v68, v28
	v_and_b32_e32 v28, 0xffff0000, v4
	v_and_b32_e32 v67, 0xffff0000, v8
	v_and_b32_e32 v66, 0xffff0000, v12
	v_pk_add_f32 v[66:67], v[66:67], v[28:29] op_sel_hi:[1,0] neg_lo:[0,1] neg_hi:[0,1]
	v_mov_b32_e32 v71, v80
	v_pk_mul_f32 v[66:67], v[66:67], v[78:79]
	v_mov_b32_e32 v80, v73
	v_add_f32_e32 v28, v66, v28
	v_add_f32_e32 v28, v28, v67
	v_add_f32_e32 v28, v28, v28
	v_mul_f32_e32 v28, 0x3fb8aa3b, v28
	v_exp_f32_e32 v28, v28
	v_add_f32_e32 v66, 1.0, v68
	v_lshlrev_b32_e32 v68, 16, v13
	v_rcp_f32_e32 v26, v26
	v_add_f32_e32 v67, 1.0, v28
	v_lshlrev_b32_e32 v28, 16, v5
	v_pk_add_f32 v[68:69], v[68:69], v[28:29] op_sel_hi:[1,0] neg_lo:[0,1] neg_hi:[0,1]
	v_rcp_f32_e32 v27, v27
	v_pk_mul_f32 v[68:69], v[68:69], v[70:71]
	v_rcp_f32_e32 v48, v48
	v_add_f32_e32 v28, v68, v28
	v_add_f32_e32 v28, v28, v69
	v_add_f32_e32 v28, v28, v28
	v_mul_f32_e32 v28, 0x3fb8aa3b, v28
	v_exp_f32_e32 v70, v28
	v_and_b32_e32 v28, 0xffff0000, v5
	v_and_b32_e32 v69, 0xffff0000, v9
	v_and_b32_e32 v68, 0xffff0000, v13
	v_pk_add_f32 v[68:69], v[68:69], v[28:29] op_sel_hi:[1,0] neg_lo:[0,1] neg_hi:[0,1]
	v_rcp_f32_e32 v49, v49
	v_pk_mul_f32 v[68:69], v[68:69], v[80:81]
	v_rcp_f32_e32 v66, v66
	v_add_f32_e32 v28, v68, v28
	v_add_f32_e32 v28, v28, v69
	v_add_f32_e32 v28, v28, v28
	v_mul_f32_e32 v28, 0x3fb8aa3b, v28
	v_exp_f32_e32 v28, v28
	v_add_f32_e32 v68, 1.0, v70
	v_rcp_f32_e32 v67, v67
	v_rcp_f32_e32 v68, v68
	v_add_f32_e32 v28, 1.0, v28
	v_rcp_f32_e32 v69, v28
	v_pk_fma_f32 v[26:27], v[26:27], 2.0, 1.0 op_sel_hi:[1,0,0] neg_lo:[1,0,0] neg_hi:[1,0,0]
	v_pk_fma_f32 v[48:49], v[48:49], 2.0, 1.0 op_sel_hi:[1,0,0] neg_lo:[1,0,0] neg_hi:[1,0,0]
	v_pk_fma_f32 v[70:71], v[66:67], 2.0, 1.0 op_sel_hi:[1,0,0] neg_lo:[1,0,0] neg_hi:[1,0,0]
	v_pk_fma_f32 v[72:73], v[68:69], 2.0, 1.0 op_sel_hi:[1,0,0] neg_lo:[1,0,0] neg_hi:[1,0,0]
	v_cvt_pk_bf16_f32 v66, v26, v27
	v_cvt_pk_bf16_f32 v67, v48, v49
	v_cvt_pk_bf16_f32 v68, v70, v71
	v_cvt_pk_bf16_f32 v69, v72, v73
	ds_write_b128 v206, v[66:69] offset:32768
	ds_read_b128 v[66:69], v47 offset:1024
	ds_read_b128 v[70:73], v47 offset:1040
	ds_read_b128 v[74:77], v47 offset:1280
	ds_read_b128 v[78:81], v47 offset:1296
	v_lshlrev_b32_e32 v26, 16, v14
	v_and_b32_e32 v27, 0xffff0000, v14
	v_lshlrev_b32_e32 v48, 16, v22
	v_and_b32_e32 v49, 0xffff0000, v22
	v_lshlrev_b32_e32 v82, 16, v18
	v_and_b32_e32 v83, 0xffff0000, v18
	v_pk_add_f32 v[48:49], v[48:49], v[26:27] neg_lo:[0,1] neg_hi:[0,1]
	s_waitcnt lgkmcnt(3)
	v_pk_fma_f32 v[48:49], v[48:49], v[66:67], v[26:27]
	v_pk_add_f32 v[26:27], v[82:83], v[26:27] neg_lo:[0,1] neg_hi:[0,1]
	v_lshlrev_b32_e32 v66, 16, v23
	s_waitcnt lgkmcnt(1)
	v_pk_fma_f32 v[26:27], v[26:27], v[74:75], v[48:49]
	v_lshlrev_b32_e32 v48, 16, v15
	v_and_b32_e32 v49, 0xffff0000, v15
	v_and_b32_e32 v67, 0xffff0000, v23
	v_lshlrev_b32_e32 v74, 16, v19
	v_and_b32_e32 v75, 0xffff0000, v19
	v_pk_add_f32 v[66:67], v[66:67], v[48:49] neg_lo:[0,1] neg_hi:[0,1]
	v_pk_fma_f32 v[66:67], v[66:67], v[68:69], v[48:49]
	v_pk_add_f32 v[48:49], v[74:75], v[48:49] neg_lo:[0,1] neg_hi:[0,1]
	v_lshlrev_b32_e32 v68, 16, v24
	v_pk_fma_f32 v[48:49], v[48:49], v[76:77], v[66:67]
	v_lshlrev_b32_e32 v66, 16, v16
	v_and_b32_e32 v67, 0xffff0000, v16
	v_and_b32_e32 v69, 0xffff0000, v24
	v_lshlrev_b32_e32 v74, 16, v20
	v_and_b32_e32 v75, 0xffff0000, v20
	v_pk_add_f32 v[68:69], v[68:69], v[66:67] neg_lo:[0,1] neg_hi:[0,1]
	v_pk_fma_f32 v[68:69], v[68:69], v[70:71], v[66:67]
	v_pk_add_f32 v[66:67], v[74:75], v[66:67] neg_lo:[0,1] neg_hi:[0,1]
	v_lshlrev_b32_e32 v70, 16, v25
	s_waitcnt lgkmcnt(0)
	v_pk_fma_f32 v[68:69], v[66:67], v[78:79], v[68:69]
	v_lshlrev_b32_e32 v66, 16, v17
	v_and_b32_e32 v67, 0xffff0000, v17
	v_and_b32_e32 v71, 0xffff0000, v25
	v_lshlrev_b32_e32 v74, 16, v21
	v_and_b32_e32 v75, 0xffff0000, v21
	v_pk_add_f32 v[70:71], v[70:71], v[66:67] neg_lo:[0,1] neg_hi:[0,1]
	v_cvt_pk_bf16_f32 v68, v68, v69
	v_pk_fma_f32 v[70:71], v[70:71], v[72:73], v[66:67]
	v_pk_add_f32 v[66:67], v[74:75], v[66:67] neg_lo:[0,1] neg_hi:[0,1]
	v_pk_fma_f32 v[70:71], v[66:67], v[80:81], v[70:71]
	v_cvt_pk_bf16_f32 v66, v26, v27
	v_cvt_pk_bf16_f32 v67, v48, v49
	v_cvt_pk_bf16_f32 v69, v70, v71
	ds_write_b128 v206, v[66:69] offset:43008
.Ltw_notfirst:
	s_waitcnt vmcnt(8)
	s_bitcmp1_b32 s0, 0
	s_cselect_b64 s[54:55], -1, 0
	v_lshrrev_b32_e32 v28, 16, v58
	v_lshrrev_b32_e32 v47, 16, v50
	v_cndmask_b32_e64 v28, v47, v28, s[54:55]
	v_lshrrev_b32_e32 v47, 16, v62
	v_lshrrev_b32_e32 v48, 16, v54
	v_lshrrev_b32_e32 v49, 16, v59
	v_lshrrev_b32_e32 v66, 16, v51
	s_cmp_eq_u32 s51, 0
	s_cbranch_scc0 .Ltw_nobar
	s_waitcnt lgkmcnt(0)
	s_barrier
.Ltw_nobar:
	v_cndmask_b32_e64 v47, v48, v47, s[54:55]
	v_cndmask_b32_e64 v48, v51, v59, s[54:55]
	v_cndmask_b32_e64 v49, v66, v49, s[54:55]
	v_add_u32_e32 v86, v181, v167
	v_perm_b32 v67, v49, v48, s47
	v_lshrrev_b32_e32 v49, 16, v63
	v_lshrrev_b32_e32 v66, 16, v55
	ds_read_b128 v[74:77], v86
	ds_read_b128 v[78:81], v86 offset:64
	v_cndmask_b32_e64 v48, v55, v63, s[54:55]
	v_cndmask_b32_e64 v49, v66, v49, s[54:55]
	v_perm_b32 v71, v49, v48, s47
	v_lshrrev_b32_e32 v49, 16, v60
	v_lshrrev_b32_e32 v66, 16, v52
	v_cndmask_b32_e64 v48, v52, v60, s[54:55]
	v_cndmask_b32_e64 v49, v66, v49, s[54:55]
	v_perm_b32 v68, v49, v48, s47
	v_lshrrev_b32_e32 v49, 16, v64
	v_lshrrev_b32_e32 v66, 16, v56
	v_cndmask_b32_e64 v48, v56, v64, s[54:55]
	v_cndmask_b32_e64 v49, v66, v49, s[54:55]
	v_perm_b32 v72, v49, v48, s47
	v_lshrrev_b32_e32 v49, 16, v61
	v_lshrrev_b32_e32 v66, 16, v53
	v_cndmask_b32_e64 v26, v50, v58, s[54:55]
	v_cndmask_b32_e64 v48, v53, v61, s[54:55]
	v_cndmask_b32_e64 v49, v66, v49, s[54:55]
	v_perm_b32 v69, v49, v48, s47
	v_perm_b32 v66, v28, v26, s47
	v_lshrrev_b32_e32 v49, 16, v65
	v_lshrrev_b32_e32 v70, 16, v57
	s_waitcnt lgkmcnt(1)
	v_mfma_f32_16x16x32_bf16 v[74:77], v[74:77], v[66:69], 0
	v_cndmask_b32_e64 v27, v54, v62, s[54:55]
	v_cndmask_b32_e64 v48, v57, v65, s[54:55]
	v_cndmask_b32_e64 v26, v70, v49, s[54:55]
	v_perm_b32 v73, v26, v48, s47
	v_perm_b32 v70, v47, v27, s47
	ds_read_b128 v[82:85], v86 offset:2624
	v_mov_b32_e32 v26, v0
	s_waitcnt lgkmcnt(1)
	v_mfma_f32_16x16x32_bf16 v[74:77], v[78:81], v[70:73], v[74:77]
	ds_read_b128 v[78:81], v86 offset:2560
	s_bfe_i32 s24, s0, 0x10000
	s_lshl_b32 s26, s35, 8
	s_waitcnt lgkmcnt(0)
	v_mfma_f32_16x16x32_bf16 v[78:81], v[78:81], v[66:69], 0
	v_mfma_f32_16x16x32_bf16 v[78:81], v[82:85], v[70:73], v[78:81]
	ds_read_b128 v[82:85], v86 offset:5120
	ds_read_b128 v[86:89], v86 offset:5184
	s_waitcnt lgkmcnt(1)
	v_mfma_f32_16x16x32_bf16 v[82:85], v[82:85], v[66:69], 0
	s_waitcnt lgkmcnt(0)
	v_mfma_f32_16x16x32_bf16 v[82:85], v[86:89], v[70:73], v[82:85]
	ds_read_b128 v[86:89], v207
	s_waitcnt lgkmcnt(0)
	v_mfma_f32_16x16x32_bf16 v[66:69], v[86:89], v[66:69], 0
	ds_read_b128 v[86:89], v207 offset:64
	s_waitcnt lgkmcnt(0)
	v_mfma_f32_16x16x32_bf16 v[66:69], v[86:89], v[70:73], v[66:69]
	ds_write2st64_b32 v182, v74, v75 offset1:1
	ds_write2st64_b32 v182, v76, v77 offset0:2 offset1:3
	ds_write2st64_b32 v182, v78, v79 offset0:16 offset1:17
	ds_write2st64_b32 v182, v80, v81 offset0:18 offset1:19
	ds_write2st64_b32 v182, v82, v83 offset0:32 offset1:33
	ds_write2st64_b32 v182, v84, v85 offset0:34 offset1:35
	s_nop 1
	ds_write2st64_b32 v182, v66, v67 offset0:48 offset1:49
	ds_write2st64_b32 v182, v68, v69 offset0:50 offset1:51
	s_waitcnt lgkmcnt(0)
	s_barrier
	s_nop 0
	v_and_b32_e32 v47, 31, v26
	v_bfe_u32 v28, v26, 5, 1
	v_mov_b32_e32 v26, s92
	v_bitop3_b32 v26, v28, s24, v26 bitop3:0x36
	v_or_b32_e32 v135, s92, v28
	v_lshlrev_b32_e32 v66, 1, v47
	v_lshlrev_b32_e32 v26, 4, v26
	v_bitop3_b32 v26, v26, v66, 48 bitop3:0x6c
	v_lshlrev_b32_e32 v67, 2, v135
	s_add_i32 s24, s26, 0
	v_lshl_add_u32 v74, v26, 2, 0
	v_sub_u32_e32 v26, 63, v67
	v_lshl_add_u32 v27, v47, 3, s24
	v_cndmask_b32_e64 v146, v67, v26, s[54:55]
	v_or_b32_e32 v234, 1, v67
	v_add_u32_e32 v27, 0x24800, v27
	v_lshlrev_b32_e32 v26, 8, v146
	v_sub_u32_e32 v68, 63, v234
	v_add_u32_e32 v147, v74, v26
	ds_read_b64 v[26:27], v27
	ds_read_b64 v[48:49], v147
	v_cndmask_b32_e64 v98, v234, v68, s[54:55]
	v_lshlrev_b32_e32 v68, 8, v98
	v_add_u32_e32 v99, v74, v68
	v_or_b32_e32 v68, 2, v67
	ds_read_b64 v[70:71], v99
	v_sub_u32_e32 v69, 63, v68
	v_cndmask_b32_e64 v94, v68, v69, s[54:55]
	s_waitcnt lgkmcnt(1)
	v_pk_add_f32 v[48:49], v[26:27], v[48:49]
	v_lshlrev_b32_e32 v69, 8, v94
	v_mul_f32_e32 v48, 0xbfb8aa3b, v48
	v_add_u32_e32 v95, v74, v69
	v_exp_f32_e32 v69, v48
	v_mul_f32_e32 v48, 0xbfb8aa3b, v49
	v_exp_f32_e32 v73, v48
	ds_read_b64 v[48:49], v95
	s_waitcnt lgkmcnt(1)
	v_pk_add_f32 v[70:71], v[26:27], v[70:71]
	v_add_f32_e32 v69, 1.0, v69
	v_mul_f32_e32 v70, 0xbfb8aa3b, v70
	v_exp_f32_e32 v70, v70
	v_rcp_f32_e32 v72, v69
	v_add_f32_e32 v69, 1.0, v73
	s_waitcnt lgkmcnt(0)
	v_pk_add_f32 v[48:49], v[26:27], v[48:49]
	v_rcp_f32_e32 v73, v69
	v_add_f32_e32 v69, 1.0, v70
	v_mul_f32_e32 v48, 0xbfb8aa3b, v48
	v_rcp_f32_e32 v70, v69
	v_exp_f32_e32 v76, v48
	v_mul_f32_e32 v48, 0xbfb8aa3b, v49
	v_or_b32_e32 v69, 3, v67
	v_exp_f32_e32 v77, v48
	v_sub_u32_e32 v48, 63, v69
	v_cndmask_b32_e64 v48, v69, v48, s[54:55]
	v_lshlrev_b32_e32 v49, 8, v48
	v_add_u32_e32 v49, v74, v49
	ds_read_b64 v[74:75], v49
	v_mul_f32_e32 v71, 0xbfb8aa3b, v71
	v_exp_f32_e32 v71, v71
	v_add_f32_e32 v76, 1.0, v76
	v_add_f32_e32 v77, 1.0, v77
	s_waitcnt lgkmcnt(0)
	v_pk_add_f32 v[26:27], v[26:27], v[74:75]
	v_add_f32_e32 v71, 1.0, v71
	v_mul_f32_e32 v26, 0xbfb8aa3b, v26
	v_mul_f32_e32 v27, 0xbfb8aa3b, v27
	v_exp_f32_e32 v26, v26
	v_exp_f32_e32 v27, v27
	v_rcp_f32_e32 v71, v71
	v_rcp_f32_e32 v76, v76
	v_rcp_f32_e32 v77, v77
	v_add_f32_e32 v26, 1.0, v26
	v_add_f32_e32 v27, 1.0, v27
	v_pk_fma_f32 v[148:149], v[72:73], s[70:71], 0 op_sel_hi:[1,0,0]
	v_rcp_f32_e32 v26, v26
	v_rcp_f32_e32 v27, v27
	v_pk_fma_f32 v[100:101], v[70:71], s[70:71], v[148:149] op_sel_hi:[1,0,1]
	v_and_b32_e32 v71, 64, v208
	v_xor_b32_e32 v70, 32, v208
	v_add_u32_e32 v71, 64, v71
	v_cmp_lt_i32_e32 vcc, v70, v71
	v_pk_fma_f32 v[96:97], v[76:77], s[70:71], v[100:101] op_sel_hi:[1,0,1]
	v_cmp_eq_u32_e64 s[52:53], 0, v28
	v_cndmask_b32_e32 v70, v208, v70, vcc
	v_pk_fma_f32 v[26:27], v[26:27], s[70:71], v[96:97] op_sel_hi:[1,0,1]
	v_lshlrev_b32_e32 v70, 2, v70
	ds_bpermute_b32 v152, v70, v26
	ds_bpermute_b32 v153, v70, v27
	s_and_saveexec_b64 s[24:25], s[52:53]
	s_cbranch_execz .LBB0_342
	v_readlane_b32 s27, v250, 25
	s_waitcnt lgkmcnt(0)
	v_pk_add_f32 v[70:71], v[26:27], v[152:153]
	v_lshl_add_u32 v28, v66, 2, s27
	ds_write_b64 v28, v[70:71] offset:32768

.LBB0_395:
	ds_read_b128 v[94:97], v215 offset:10240
	ds_read_b128 v[98:101], v215 offset:11264
	ds_read_b128 v[102:105], v215 offset:12288
	ds_read_b128 v[106:109], v215 offset:13312
	s_waitcnt lgkmcnt(11)
	v_cvt_pk_bf16_f32 v48, v48, v49
	s_waitcnt lgkmcnt(3)
	v_cvt_pk_bf16_f32 v94, v94, v95
	v_cvt_pk_bf16_f32 v95, v96, v97
	v_cvt_pk_bf16_f32 v49, v68, v69
	v_mov_b32_e32 v26, v78
	v_mov_b32_e32 v27, v79
	v_mov_b32_e32 v74, v80
	v_mov_b32_e32 v75, v81
	v_mfma_f32_16x16x16_bf16 v[78:81], v[94:95], v[48:49], 0
	v_mov_b32_e32 v28, v29
	s_waitcnt lgkmcnt(2)
	v_cvt_pk_bf16_f32 v96, v98, v99
	v_cvt_pk_bf16_f32 v97, v100, v101
	s_waitcnt lgkmcnt(1)
	v_cvt_pk_bf16_f32 v98, v102, v103
	s_nop 1
	v_xor_b32_e32 v47, 0x80000000, v79
	v_xor_b32_e32 v48, 0x80000000, v78
	v_cvt_pk_bf16_f32 v78, v48, v47
	v_xor_b32_e32 v47, 0x80000000, v80
	v_xor_b32_e32 v48, 0x80000000, v81
	v_cvt_pk_bf16_f32 v79, v47, v48
	v_mov_b32_e32 v80, v29
	v_mov_b32_e32 v81, v29
	v_cvt_pk_bf16_f32 v99, v104, v105
	v_mov_b32_e32 v68, v29
	v_mfma_f32_16x16x32_bf16 v[90:93], v[26:29], v[78:81], v[90:93]
	v_mov_b32_e32 v69, v29
	s_waitcnt lgkmcnt(0)
	v_cvt_pk_bf16_f32 v100, v106, v107
	v_cvt_pk_bf16_f32 v101, v108, v109
	s_nop 3
	v_cvt_pk_bf16_f32 v26, v90, v91
	v_cvt_pk_bf16_f32 v27, v92, v93
	s_andn2_b64 vcc, exec, s[62:63]
	s_nop 0
	v_mfma_f32_16x16x16_bf16 v[90:93], v[96:97], v[26:27], 0
	s_nop 7
	v_xor_b32_e32 v26, 0x80000000, v91
	v_xor_b32_e32 v27, 0x80000000, v90
	v_cvt_pk_bf16_f32 v80, v27, v26
	v_xor_b32_e32 v26, 0x80000000, v92
	v_xor_b32_e32 v27, 0x80000000, v93
	v_cvt_pk_bf16_f32 v81, v26, v27
	ds_write2_b64 v216, v[78:79], v[80:81] offset1:4
	s_nop 0
	v_mfma_f32_16x16x32_bf16 v[74:77], v[74:77], v[78:81], v[86:89]
	v_mfma_f32_16x16x32_bf16 v[70:73], v[70:73], v[78:81], v[82:85]
	s_nop 6
	v_cvt_pk_bf16_f32 v26, v74, v75
	v_cvt_pk_bf16_f32 v27, v76, v77
	s_nop 1
	v_mfma_f32_16x16x16_bf16 v[74:77], v[98:99], v[26:27], 0
	s_nop 7
	v_xor_b32_e32 v26, 0x80000000, v75
	v_xor_b32_e32 v27, 0x80000000, v74
	v_cvt_pk_bf16_f32 v26, v27, v26
	v_xor_b32_e32 v27, 0x80000000, v76
	v_xor_b32_e32 v28, 0x80000000, v77
	v_cvt_pk_bf16_f32 v27, v27, v28
	v_mov_b32_e32 v28, v29
	s_nop 1
	v_mfma_f32_16x16x32_bf16 v[66:69], v[66:69], v[26:29], v[70:73]
	s_nop 7
	v_cvt_pk_bf16_f32 v48, v66, v67
	v_cvt_pk_bf16_f32 v49, v68, v69
	s_nop 1
	v_mfma_f32_16x16x16_bf16 v[66:69], v[100:101], v[48:49], 0
	s_nop 7
	v_xor_b32_e32 v28, 0x80000000, v67
	v_xor_b32_e32 v47, 0x80000000, v66
	v_cvt_pk_bf16_f32 v48, v47, v28
	v_xor_b32_e32 v28, 0x80000000, v68
	v_xor_b32_e32 v47, 0x80000000, v69
	v_cvt_pk_bf16_f32 v49, v28, v47
	ds_write2_b64 v216, v[26:27], v[48:49] offset0:8 offset1:12
	s_waitcnt lgkmcnt(0)
	s_barrier
	v_readfirstlane_b32 s36, v0
	s_cmp_lt_u32 s36, 0x100
	s_cbranch_scc0 .Ltw_prod
	s_waitcnt vmcnt(0)
	s_branch .Ltw_do
.Ltw_prod:
	ds_read_b128 v[74:77], v217
	ds_read_b128 v[78:81], v227
	ds_read_b128 v[70:73], v217 offset:64
	v_add_u32_e32 v26, v192, v196
	ds_read_b128 v[82:85], v228
	ds_read_b128 v[86:89], v26
	ds_read_b128 v[66:69], v204
	s_waitcnt lgkmcnt(1)
	v_mfma_f32_16x16x32_bf16 v[90:93], v[74:77], v[86:89], 0
	v_cndmask_b32_e64 v27, 0, 1, s[62:63]
	v_cmp_ne_u32_e64 s[56:57], 1, v27
	s_cbranch_vccnz .LBB0_397
	ds_read_b128 v[94:97], v26 offset:64
	s_waitcnt lgkmcnt(0)
	v_mfma_f32_16x16x32_bf16 v[90:93], v[70:73], v[94:97], v[90:93]
